# speedup vs baseline: 1.0342x; 1.0338x over previous
; #define LAS __attribute__((address_space(3)))
; __global__ void __launch_bounds__(NTHR, 2) hymba_fwd(Args args) {
;     extern __shared__ __attribute__((aligned(16))) unsigned char lds_raw[];
;     LAS unsigned char* lds = (LAS unsigned char*)lds_raw;
;     LAS float* ldsf = (LAS float*)lds;
;     cg::grid_group grid = cg::this_grid();
;     volatile LAS unsigned* bar_st = (volatile LAS unsigned*)(lds + 131072 + 512);
;     if (threadIdx.x < 2) bar_st[threadIdx.x] = 0u;
;     __syncthreads();
;     XcdBarrier xbar = xcd_barrier_post((unsigned*)(args.ws + WS_BAR), bar_st);
_Z9hymba_fwd4Args:
	s_add_u32 s4, s0, 0x188
	v_writelane_b32 v253, s2, 0
	s_load_dwordx4 s[52:55], s[0:1], 0x178
	s_load_dwordx2 s[2:3], s[0:1], 0x188
	v_and_b32_e32 v172, 0x3ff, v0
	v_cmp_gt_u32_e32 vcc, 2, v172
	s_waitcnt lgkmcnt(0)
	s_lshl_b32 s55, s55, 1
	s_sub_i32 s55, s55, 1
	v_writelane_b32 v253, s2, 1
	s_nop 1
	v_writelane_b32 v253, s3, 2
	v_writelane_b32 v253, s0, 3
	s_addc_u32 s5, s1, 0
	s_nop 0
	v_writelane_b32 v253, s1, 4
	s_and_saveexec_b64 s[0:1], vcc
	v_lshl_add_u32 v1, v172, 2, 0
	v_add_u32_e32 v1, 0x20200, v1
	v_mov_b32_e32 v2, 0
	ds_write_b32 v1, v2
	s_or_b64 exec, exec, s[0:1]
	s_waitcnt lgkmcnt(0)
	s_barrier
	s_add_u32 s0, s52, 0x29d00000
	s_getreg_b32 s2, hwreg(HW_REG_XCC_ID, 0, 4)
	s_addc_u32 s1, s53, 0
	s_and_b32 s10, s2, 15
	v_cmp_eq_u32_e64 s[6:7], 0, v172
	s_mov_b64 s[2:3], exec
	s_nop 0
	v_writelane_b32 v253, s6, 5
	s_nop 1
	v_writelane_b32 v253, s7, 6
	s_and_b64 s[6:7], s[2:3], s[6:7]
	s_mov_b64 exec, s[6:7]
	s_cbranch_execz .LBB0_5
	s_mov_b64 s[6:7], exec
	v_mbcnt_lo_u32_b32 v1, s6, 0
	v_mbcnt_hi_u32_b32 v1, s7, v1
	v_cmp_eq_u32_e32 vcc, 0, v1
	s_and_b64 s[8:9], exec, vcc
	s_mov_b64 exec, s[8:9]
	s_cbranch_execz .LBB0_5
	s_lshl_b32 s8, s10, 8
	s_bcnt1_i32_b64 s6, s[6:7]
	v_mov_b32_e32 v1, s8
	v_mov_b32_e32 v2, s6
	global_atomic_add v1, v2, s[0:1] offset:1024

; __global__ void __launch_bounds__(NTHR, 2) hymba_fwd(Args args) {
;     ...
;     for (int ph = lo; ph < hi; ++ph) {
;         int l = ph / NPH; const int k = ph % NPH;
;         if (k == 3 || k == 11) continue;
;         asm volatile("" : "+s"(l));
;         int G = gridDim.x, bid = blockIdx.x; asm volatile("" : "+s"(G), "+s"(bid));
;         typedef __attribute__((address_space(4))) const unsigned char* kptr_t;
;         kptr_t kp = (kptr_t)__builtin_amdgcn_kernarg_segment_ptr(); asm volatile("" : "+s"(kp));
;         int tid = threadIdx.x; asm volatile("" : "+v"(tid));
;         const int lane = tid & 63, wave = __builtin_amdgcn_readfirstlane(tid >> 6);
;         const int gw = bid * NWAVES + wave, NGW = G * NWAVES;
;         unsigned char* ws = *(unsigned char* const __attribute__((address_space(4)))*)(kp + 376);
;         float* xout = *(float* const __attribute__((address_space(4)))*)(kp + 368);
.LBB0_20:
	s_lshr_b32 s5, s54, 1
	s_mul_hi_i32 s0, s5, 0x92492493
	s_add_i32 s0, s0, s5
	s_lshr_b32 s1, s0, 31
	s_ashr_i32 s0, s0, 3
	s_add_i32 s4, s0, s1
	s_mul_i32 s0, s4, 14
	s_sub_i32 s5, s5, s0
	s_cmp_eq_u32 s5, 1
	s_cselect_b32 s0, 1, 0
	s_cmp_eq_u32 s5, 4
	s_cselect_b32 s1, 1, 0
	s_or_b32 s0, s0, s1
	s_cmp_eq_u32 s5, 7
	s_cselect_b32 s1, 1, 0
	s_or_b32 s0, s0, s1
	s_bitcmp1_b32 s54, 0
	s_cbranch_scc1 .Lhdr_rep1
	v_writelane_b32 v255, s0, 62
	s_mov_b32 s0, 0
	s_mov_b32 s1, 0xa07f
	v_writelane_b32 v255, s0, 61
	v_writelane_b32 v255, s1, 59
	s_movk_i32 s0, 0x2c00
	s_mov_b32 s1, 0x9fff
	v_writelane_b32 v255, s0, 57
	v_writelane_b32 v255, s1, 56
	s_branch .Lhdr_common
.Lhdr_rep1:
	s_cmp_eq_u32 s0, 0
	s_mov_b64 s[0:1], -1
	s_cbranch_scc1 .LBB0_24
	s_mov_b32 s0, 0x5600
	s_mov_b32 s1, 0x7fff
	s_cmp_eq_u32 s5, 1
	s_cmov_b32 s0, 0x2c00
	s_cmov_b32 s1, 0x55ff
	s_cmp_eq_u32 s5, 7
	s_cmov_b32 s0, 0x8000
	s_cmov_b32 s1, 0x9fff
	v_writelane_b32 v255, s0, 60
	v_writelane_b32 v255, s1, 59
	s_mov_b32 s0, 0x80
	s_cmov_b32 s0, 64
	s_mov_b32 s1, 1
	v_writelane_b32 v255, s0, 58
	v_writelane_b32 v255, s1, 61
	s_mov_b32 s0, 0
	s_mov_b32 s1, 0x7fffffff
	v_writelane_b32 v255, s0, 62
	v_writelane_b32 v255, s1, 57
	v_writelane_b32 v255, s0, 56
	s_mov_b32 s5, 0
.Lhdr_common:
	s_and_b32 s0, s5, -9
	s_cmp_lg_u32 s0, 3
	s_mov_b64 s[0:1], -1
	s_cbranch_scc0 .LBB0_24
	v_readlane_b32 s0, v253, 1
	v_readlane_b32 s1, v253, 2
	s_mov_b32 s45, s0
	v_readlane_b32 s0, v253, 0
	v_writelane_b32 v254, s5, 29
	s_mov_b32 s44, s0
	v_readlane_b32 s0, v253, 3
	v_writelane_b32 v254, s4, 30
	v_readlane_b32 s1, v253, 4
	v_mov_b32_e32 v148, v172
	v_writelane_b32 v254, s5, 31
	v_writelane_b32 v254, s0, 32
	s_mov_b64 s[10:11], s[54:55]
	s_load_dwordx4 s[16:19], s[0:1], 0x170
	v_writelane_b32 v254, s1, 33
	v_readfirstlane_b32 s28, v148
	v_readlane_b32 s0, v254, 29
	v_writelane_b32 v254, s8, 34
	s_mov_b64 s[6:7], -1
	s_mov_b64 s[4:5], 0
	v_writelane_b32 v254, s9, 35
	v_writelane_b32 v254, s10, 36
	v_writelane_b32 v254, s11, 37
	v_writelane_b32 v254, s45, 38
	s_cmp_lt_i32 s0, 1
	s_mov_b64 s[0:1], 0
	v_writelane_b32 v254, s44, 39
	s_cbranch_scc1 .LBB0_46
	v_readlane_b32 s6, v254, 29
	s_cmp_gt_i32 s6, 11
	s_cbranch_scc0 .LBB0_25
	s_cmp_eq_u32 s6, 12
	s_mov_b64 s[0:1], -1
	s_cselect_b64 s[6:7], -1, 0
	s_cbranch_execz .LBB0_26
	s_branch .LBB0_27

; #define LAS __attribute__((address_space(3)))
; __global__ void __launch_bounds__(NTHR, 2) hymba_fwd(Args args) {
;     ...
;             FILL_L();
;             bf16* W13A = WSP(bf16, WS_W13A); bf16* W2A = WSP(bf16, WS_W2A); bf16* WIN = WSP(bf16, WS_WIN); bf16* WOUT = WSP(bf16, WS_WOUT); bf16* W13B = WSP(bf16, WS_W13B); bf16* W2B = WSP(bf16, WS_W2B); bf16* WGLU = WSP(bf16, WS_GLU);
;             LAS float* scr = (LAS float*)(lds + wave * 16384);
;             constexpr int I_UP = (D / 64) * (FF / 32), I_DN = (FF / 64) * (D / 32), I_IN = (D / 64) * (DIN / 32), I_OUT = (D / 64) * (D / 32), I_GLU = (GW / 64) * (GW / 32);
;             constexpr int NITEMS = 4 * I_UP + 2 * I_DN + I_IN + I_OUT + I_GLU;
;             for (int it = gw; it < NITEMS; it += NGW) {
;                 int r = it;
;                 if (r < I_UP) { transpose_item(L.ffn1_w1, D, FF, W13A, 1, scr, r, lane); continue; } r -= I_UP;
.LBB0_555:
	v_readlane_b32 s0, v254, 32
	s_and_b64 vcc, exec, s[4:5]
	v_readlane_b32 s1, v254, 33
	s_cbranch_vccz .LBB0_627
	s_waitcnt lgkmcnt(0)
	s_load_dwordx2 s[16:17], s[0:1], 0x8
	s_load_dwordx4 s[20:23], s[0:1], 0xa8
	s_load_dwordx8 s[4:11], s[0:1], 0xc0
	v_readlane_b32 s0, v255, 61
	s_cmp_eq_u32 s0, 0
	s_cbranch_scc1 .Lp0_norm
	v_readlane_b32 s0, v254, 39
	v_readlane_b32 s1, v255, 58
	s_sub_i32 s0, s0, s1
	s_cmp_lt_i32 s0, 0
	s_cbranch_scc1 .LBB0_627
	s_lshl_b32 s0, s0, 3
	v_readlane_b32 s12, v254, 44
	s_add_i32 s0, s0, s12
	v_readlane_b32 s12, v255, 60
	s_add_i32 s0, s0, s12
	v_readlane_b32 s12, v254, 38
	s_sub_i32 s1, s12, s1
	s_lshl_b32 s1, s1, 3
	v_writelane_b32 v254, s0, 40
	v_writelane_b32 v254, s1, 42
.Lp0_norm:
	v_readlane_b32 s0, v254, 30
	v_readlane_b32 s1, v254, 31
	s_ashr_i32 s1, s0, 31
	v_writelane_b32 v254, s0, 30
	s_nop 1
	v_writelane_b32 v254, s1, 31
	s_nop 0
	v_readlane_b32 s0, v254, 40
	v_readlane_b32 s1, v255, 59
	s_cmp_gt_i32 s0, s1
	v_readlane_b32 s48, v254, 42
	v_readlane_b32 s1, v254, 41
	v_readlane_b32 s49, v254, 43
	s_cbranch_scc1 .LBB0_591
	v_readlane_b32 s38, v254, 32
	v_readlane_b32 s0, v254, 44
	v_readlane_b32 s39, v254, 33
	s_lshl_b32 s12, s0, 14
	s_load_dwordx2 s[0:1], s[38:39], 0x168
	s_load_dwordx4 s[24:27], s[38:39], 0x158
	v_readlane_b32 s46, v254, 30
	s_add_i32 s12, s12, 0
	s_mul_i32 s41, s46, 0x2c00000
	s_mul_hi_i32 s40, s46, 0x2c00000
	s_waitcnt lgkmcnt(0)
	s_add_u32 s0, s0, s41
	s_addc_u32 s1, s1, s40
	s_add_u32 s14, s26, s41
	s_addc_u32 s15, s27, s40
	s_load_dwordx2 s[26:27], s[38:39], 0x148
	s_load_dwordx2 s[30:31], s[38:39], 0x78
	s_load_dwordx2 s[36:37], s[38:39], 0x30
	v_readlane_b32 s47, v254, 31
	s_add_u32 s28, s24, s41
	s_addc_u32 s29, s25, s40
	s_lshl_b64 s[24:25], s[46:47], 24
	s_waitcnt lgkmcnt(0)
	s_add_u32 s34, s26, s24
	s_addc_u32 s35, s27, s25
	s_lshl_b64 s[24:25], s[46:47], 20
	s_add_u32 s30, s30, s24
	s_addc_u32 s31, s31, s25
	s_load_dwordx4 s[24:27], s[38:39], 0x10
	s_nop 0
	s_load_dwordx2 s[38:39], s[38:39], 0x20
	s_mul_i32 s43, s46, 0x2800000
	s_waitcnt vmcnt(5)
	v_lshlrev_b32_e32 v2, 3, v188
	s_mul_hi_i32 s42, s46, 0x2800000
	s_add_u32 s36, s36, s43
	v_lshrrev_b32_e32 v32, 3, v188
	v_lshlrev_b32_e32 v0, 4, v188
	v_and_b32_e32 v2, 56, v2
	s_addc_u32 s37, s37, s42
	v_and_b32_e32 v30, 0x70, v0
	v_mov_b32_e32 v31, v144
	s_waitcnt vmcnt(4)
	v_mul_u32_u24_e32 v6, 0x84, v2
	v_lshlrev_b32_e32 v2, 1, v2
	v_mov_b32_e32 v3, v144
	v_lshlrev_b32_e32 v7, 2, v32
	s_waitcnt lgkmcnt(0)
	s_add_u32 s38, s38, s41
	v_lshl_add_u64 v[2:3], s[18:19], 0, v[2:3]
	v_add3_u32 v38, s12, v6, v7
	v_lshl_add_u64 v[6:7], s[0:1], 0, v[30:31]
	s_mov_b64 s[0:1], 0x8a00000
	s_addc_u32 s39, s39, s40
	s_waitcnt vmcnt(3)
	v_lshl_add_u64 v[8:9], v[2:3], 0, s[0:1]
	s_mov_b64 s[0:1], 0x5e00000
	s_add_u32 s26, s26, s41
	s_waitcnt vmcnt(2)
	v_lshl_add_u64 v[12:13], v[2:3], 0, s[0:1]
	s_mov_b64 s[0:1], 0x5600000
	s_addc_u32 s27, s27, s40
	s_waitcnt vmcnt(1)
	v_lshl_add_u64 v[18:19], v[2:3], 0, s[0:1]
	s_mov_b64 s[0:1], 0x4200000
	s_add_u32 s24, s24, s41
	s_waitcnt vmcnt(0)
	v_lshl_add_u64 v[22:23], v[2:3], 0, s[0:1]
	s_mov_b64 s[0:1], 0x2c00000
	s_addc_u32 s25, s25, s40
	v_lshl_add_u64 v[0:1], s[30:31], 0, v[30:31]
	s_mov_b64 s[30:31], 0xa000000
	v_lshl_add_u64 v[26:27], v[2:3], 0, s[0:1]
	v_readlane_b32 s0, v254, 40
	v_add_u32_e32 v33, s12, v30
	v_mul_u32_u24_e32 v34, 0x84, v32
	v_or_b32_e32 v35, 8, v32
	v_or_b32_e32 v36, 16, v32
	v_or_b32_e32 v37, 24, v32
	v_lshl_add_u64 v[4:5], v[2:3], 0, s[30:31]
	v_lshl_add_u64 v[10:11], s[14:15], 0, v[30:31]
	v_lshl_add_u64 v[14:15], s[28:29], 0, v[30:31]
	v_lshl_add_u64 v[16:17], s[34:35], 0, v[30:31]
	v_lshl_add_u64 v[20:21], s[36:37], 0, v[30:31]
	v_lshl_add_u64 v[24:25], s[38:39], 0, v[30:31]
	v_lshl_add_u64 v[28:29], s[26:27], 0, v[30:31]
	v_lshl_add_u64 v[30:31], s[24:25], 0, v[30:31]
	s_lshl_b32 s24, s0, 5
	s_lshl_b32 s25, s48, 5
	s_lshl_b32 s26, s0, 6
	s_lshl_b32 s27, s48, 6
	s_lshl_b32 s28, s0, 2
	s_lshl_b32 s29, s48, 2
	s_mov_b32 s30, s0
	v_readlane_b32 s1, v254, 41
	s_branch .LBB0_559
.LBB0_558:
	v_readlane_b32 s0, v254, 42
	s_add_i32 s30, s30, s0
	s_add_i32 s24, s24, s25
	s_add_i32 s26, s26, s27
	s_add_i32 s28, s28, s29
	v_readlane_b32 s0, v255, 59
	s_cmp_gt_i32 s30, s0
	v_readlane_b32 s1, v254, 43
	s_cbranch_scc1 .LBB0_591
; #define LAS __attribute__((address_space(3)))
; __device__ __forceinline__ void transpose_item(const float* W, int K, int N, bf16* WT, int mode, LAS float* scr, int item, int lane) {
;     const int nblk = N / 32, kb = item / nblk, nb = item % nblk, k0 = 64 * kb, n0 = 32 * nb;
;     {
;         f32x4 v[8];
; #pragma unroll
;         for (int i = 0; i < 8; ++i) v[i] = __builtin_nontemporal_load((const f32x4*)(W + (size_t)(k0 + 8 * i + (lane >> 3)) * N + n0 + (lane & 7) * 4));
;         KEEP8(v);
; #pragma unroll
;         for (int i = 0; i < 8; ++i) { LAS float* d = scr + (8 * i + (lane >> 3)) * 33 + (lane & 7) * 4; d[0] = v[i].x; d[1] = v[i].y; d[2] = v[i].z; d[3] = v[i].w; }
;     }
;     LDS_WAIT(); asm volatile("" ::: "memory");
;     const int c = lane & 7;
;     const int r0 = (mode == 0) ? n0 : ((n0 >> 7) * 256 + (n0 & 127) + (mode == 2 ? 128 : 0));
; #pragma unroll
;     for (int j = 0; j < 4; ++j) { const int n = (lane >> 3) + 8 * j; const LAS float* s = scr + (8 * c) * 33 + n;
;         u32x4 o; o.x = pg8::cvt_pk_bf16(s[0 * 33], s[1 * 33]); o.y = pg8::cvt_pk_bf16(s[2 * 33], s[3 * 33]); o.z = pg8::cvt_pk_bf16(s[4 * 33], s[5 * 33]); o.w = pg8::cvt_pk_bf16(s[6 * 33], s[7 * 33]);
;         *(u32x4*)(WT + (size_t)(r0 + n) * K + k0 + 8 * c) = o; }
;     LDS_WAIT(); asm volatile("" ::: "memory");
; }
; __global__ void __launch_bounds__(NTHR, 2) hymba_fwd(Args args) {
;     ...
;                 if (r < I_UP) { transpose_item(L.ffn1_w1, D, FF, W13A, 1, scr, r, lane); continue; } r -= I_UP;
;                 if (r < I_UP) { transpose_item(L.ffn1_w3, D, FF, W13A, 2, scr, r, lane); continue; } r -= I_UP;
;                 if (r < I_DN) { transpose_item(L.ffn1_w2, FF, D, W2A, 0, scr, r, lane); continue; } r -= I_DN;
;                 if (r < I_IN) { transpose_item(L.w_in, D, DIN, WIN, 0, scr, r, lane); continue; } r -= I_IN;
;                 if (r < I_OUT) { transpose_item(L.w_out, D, D, WOUT, 0, scr, r, lane); continue; } r -= I_OUT;
;                 if (r < I_UP) { transpose_item(L.ffn2_w1, D, FF, W13B, 1, scr, r, lane); continue; } r -= I_UP;
;                 if (r < I_UP) { transpose_item(L.ffn2_w3, D, FF, W13B, 2, scr, r, lane); continue; } r -= I_UP;
;                 if (r < I_DN) { transpose_item(L.ffn2_w2, FF, D, W2B, 0, scr, r, lane); continue; } r -= I_DN;
;                 transpose_item(L.s5_gw, GW, GW, WGLU, 0, scr, r, lane);
.LBB0_559:
	v_readlane_b32 s0, v255, 57
	v_readlane_b32 s1, v255, 56
	s_cmp_ge_i32 s30, s0
	s_cselect_b32 s0, 1, 0
	s_cmp_le_i32 s30, s1
	s_cselect_b32 s1, 1, 0
	s_and_b32 s0, s0, s1
	s_cmp_lg_u32 s0, 0
	s_cbranch_scc1 .LBB0_558
	s_cmpk_gt_i32 s30, 0x15ff
	s_mov_b64 s[0:1], -1
	s_cbranch_scc0 .LBB0_589
	s_cmpk_gt_u32 s30, 0x2bff
	s_cbranch_scc0 .LBB0_586
	s_cmpk_gt_u32 s30, 0x41ff
	s_cbranch_scc0 .LBB0_583
	s_cmpk_gt_u32 s30, 0x55ff
	s_cbranch_scc0 .LBB0_580
	s_cmpk_gt_u32 s30, 0x5dff
	s_cbranch_scc0 .LBB0_577
	s_cmpk_gt_u32 s30, 0x73ff
	s_cbranch_scc0 .LBB0_574
	s_cmpk_gt_u32 s30, 0x89ff
	s_cbranch_scc0 .LBB0_571
	s_cmpk_gt_u32 s30, 0x9fff
	s_cbranch_scc0 .LBB0_568
	s_and_b32 s1, s28, 0x3c0
	s_and_b32 s0, s24, 0x1e0
	v_or_b32_e32 v39, s1, v32
	s_lshl_b32 s12, s0, 2
	v_lshl_add_u64 v[40:41], v[0:1], 0, s[12:13]
	v_lshlrev_b32_e32 v42, 11, v39
	v_mov_b32_e32 v43, v144
	v_lshl_add_u64 v[64:65], v[40:41], 0, v[42:43]
	v_add_co_u32_e32 v44, vcc, 0x4000, v64
	s_mov_b32 s12, 0x10000
	s_nop 0
	v_addc_co_u32_e32 v45, vcc, 0, v65, vcc
	v_add_co_u32_e32 v48, vcc, 0x8000, v64
	global_load_dwordx4 v[40:43], v[64:65], off nt
	s_nop 0
	global_load_dwordx4 v[44:47], v[44:45], off nt
	v_addc_co_u32_e32 v49, vcc, 0, v65, vcc
	v_add_co_u32_e32 v52, vcc, 0xc000, v64
	v_add_u32_e32 v39, v33, v34
	s_nop 0
	v_addc_co_u32_e32 v53, vcc, 0, v65, vcc
	v_add_co_u32_e32 v56, vcc, s12, v64
	s_mov_b32 s12, 0x14000
	s_nop 0
	v_addc_co_u32_e32 v57, vcc, 0, v65, vcc
	v_add_co_u32_e32 v60, vcc, s12, v64
	s_mov_b32 s12, 0x18000
	s_nop 0
	v_addc_co_u32_e32 v61, vcc, 0, v65, vcc
	v_add_co_u32_e32 v66, vcc, s12, v64
	s_mov_b32 s12, 0x1c000
	s_nop 0
	v_addc_co_u32_e32 v67, vcc, 0, v65, vcc
	v_add_co_u32_e32 v68, vcc, s12, v64
	global_load_dwordx4 v[48:51], v[48:49], off nt
	s_nop 0
	global_load_dwordx4 v[52:55], v[52:53], off nt
	v_addc_co_u32_e32 v69, vcc, 0, v65, vcc
	global_load_dwordx4 v[56:59], v[56:57], off nt
	s_nop 0
	global_load_dwordx4 v[60:63], v[60:61], off nt
	s_nop 0
	global_load_dwordx4 v[64:67], v[66:67], off nt
	s_nop 0
	global_load_dwordx4 v[68:71], v[68:69], off nt
	v_add_u32_e32 v72, 0x420, v39
	v_add_u32_e32 v73, 0x428, v39
	v_add_u32_e32 v74, 0x840, v39
	v_add_u32_e32 v75, 0x848, v39
	v_add_u32_e32 v76, 0xc60, v39
	v_add_u32_e32 v77, 0xc68, v39
	v_add_u32_e32 v78, 0x1080, v39
	v_add_u32_e32 v79, 0x1088, v39
	v_add_u32_e32 v80, 0x14a0, v39
	v_add_u32_e32 v81, 0x14a8, v39
	v_add_u32_e32 v82, 0x18c0, v39
	v_add_u32_e32 v83, 0x18c8, v39
	v_add_u32_e32 v84, 0x1ce0, v39
	v_add_u32_e32 v85, 0x1ce8, v39
	s_lshl_b32 s12, s1, 1
	s_waitcnt vmcnt(0)
	ds_write2_b32 v39, v40, v41 offset1:1
	ds_write2_b32 v39, v42, v43 offset0:2 offset1:3
	ds_write2_b32 v72, v44, v45 offset1:1
	ds_write2_b32 v73, v46, v47 offset1:1
	ds_write2_b32 v74, v48, v49 offset1:1
	ds_write2_b32 v75, v50, v51 offset1:1
	ds_write2_b32 v76, v52, v53 offset1:1
	ds_write2_b32 v77, v54, v55 offset1:1
	ds_write2_b32 v78, v56, v57 offset1:1
	ds_write2_b32 v79, v58, v59 offset1:1
	ds_write2_b32 v80, v60, v61 offset1:1
	ds_write2_b32 v81, v62, v63 offset1:1
	ds_write2_b32 v82, v64, v65 offset1:1
	ds_write2_b32 v83, v66, v67 offset1:1
	ds_write2_b32 v84, v68, v69 offset1:1
	ds_write2_b32 v85, v70, v71 offset1:1
	s_waitcnt lgkmcnt(0)
	ds_read2_b32 v[40:41], v38 offset1:33
	s_waitcnt lgkmcnt(0)
	v_cvt_pk_bf16_f32 v40, v40, v41
	ds_read2_b32 v[42:43], v38 offset0:66 offset1:99
	v_or_b32_e32 v39, s0, v32
	s_waitcnt lgkmcnt(0)
	v_cvt_pk_bf16_f32 v41, v42, v43
	ds_read2_b32 v[42:43], v38 offset0:132 offset1:165
	v_mov_b32_e32 v47, v144
	v_lshlrev_b32_e32 v46, 10, v39
	v_lshl_add_u64 v[48:49], v[4:5], 0, s[12:13]
	s_waitcnt lgkmcnt(0)
	v_cvt_pk_bf16_f32 v42, v42, v43
	ds_read2_b32 v[44:45], v38 offset0:198 offset1:231
	s_waitcnt lgkmcnt(0)
	v_cvt_pk_bf16_f32 v43, v44, v45
	v_lshl_add_u64 v[46:47], v[48:49], 0, v[46:47]
	ds_read2_b32 v[44:45], v38 offset0:8 offset1:41
	global_store_dwordx4 v[46:47], v[40:43], off
	v_or_b32_e32 v39, s0, v35
	v_mov_b32_e32 v47, v144
	s_waitcnt lgkmcnt(0)
	v_cvt_pk_bf16_f32 v40, v44, v45
	ds_read2_b32 v[42:43], v38 offset0:74 offset1:107
	s_waitcnt lgkmcnt(0)
	v_cvt_pk_bf16_f32 v41, v42, v43
	ds_read2_b32 v[42:43], v38 offset0:140 offset1:173
	v_lshlrev_b32_e32 v46, 10, v39
	s_waitcnt lgkmcnt(0)
	v_cvt_pk_bf16_f32 v42, v42, v43
	ds_read2_b32 v[44:45], v38 offset0:206 offset1:239
	s_waitcnt lgkmcnt(0)
	v_cvt_pk_bf16_f32 v43, v44, v45
	v_lshl_add_u64 v[46:47], v[48:49], 0, v[46:47]
	ds_read2_b32 v[44:45], v38 offset0:16 offset1:49
	global_store_dwordx4 v[46:47], v[40:43], off
	v_or_b32_e32 v39, s0, v36
	v_mov_b32_e32 v47, v144
	s_waitcnt lgkmcnt(0)
	v_cvt_pk_bf16_f32 v40, v44, v45
	ds_read2_b32 v[42:43], v38 offset0:82 offset1:115
	s_waitcnt lgkmcnt(0)
	v_cvt_pk_bf16_f32 v41, v42, v43
	ds_read2_b32 v[42:43], v38 offset0:148 offset1:181
	v_lshlrev_b32_e32 v46, 10, v39
	s_waitcnt lgkmcnt(0)
	v_cvt_pk_bf16_f32 v42, v42, v43
	ds_read2_b32 v[44:45], v38 offset0:214 offset1:247
	s_waitcnt lgkmcnt(0)
	v_cvt_pk_bf16_f32 v43, v44, v45
	v_lshl_add_u64 v[46:47], v[48:49], 0, v[46:47]
	ds_read2_b32 v[44:45], v38 offset0:24 offset1:57
	global_store_dwordx4 v[46:47], v[40:43], off
	v_or_b32_e32 v39, s0, v37
	v_mov_b32_e32 v47, v144
	s_waitcnt lgkmcnt(0)
	v_cvt_pk_bf16_f32 v40, v44, v45
	ds_read2_b32 v[42:43], v38 offset0:90 offset1:123
	s_waitcnt lgkmcnt(0)
	v_cvt_pk_bf16_f32 v41, v42, v43
	ds_read2_b32 v[42:43], v38 offset0:156 offset1:189
	s_waitcnt lgkmcnt(0)
	v_cvt_pk_bf16_f32 v42, v42, v43
	ds_read2_b32 v[44:45], v38 offset0:222 offset1:255
	v_lshlrev_b32_e32 v46, 10, v39
	s_waitcnt lgkmcnt(0)
	v_cvt_pk_bf16_f32 v43, v44, v45
	v_lshl_add_u64 v[44:45], v[48:49], 0, v[46:47]
	global_store_dwordx4 v[44:45], v[40:43], off
	s_waitcnt lgkmcnt(0)
	s_mov_b64 s[0:1], 0

; __global__ void __launch_bounds__(NTHR, 2) hymba_fwd(Args args) {
;     ...
;             {
;                 float* LT = WSP(float, WS_LORA);
;                 for (int i = bid * NTHR + tid; i < LT_TOTAL; i += G * NTHR) {
;                     const float* src; int N_, K_, o;
;                     if (i < LT_AA) { src = L.rw_wa; N_ = 64; K_ = GW; o = i; } else if (i < LT_GA) { src = L.rw_aa; N_ = 64; K_ = GW; o = i - LT_AA; } else if (i < LT_WB) { src = L.rw_ga; N_ = 128; K_ = GW; o = i - LT_GA; }
;                     else if (i < LT_AB) { src = L.rw_wb; N_ = GW; K_ = 64; o = i - LT_WB; } else if (i < LT_GB) { src = L.rw_ab; N_ = GW; K_ = 64; o = i - LT_AB; } else { src = L.rw_gb; N_ = GW; K_ = 128; o = i - LT_GB; }
;                     const int n_ = o / K_, k_ = o % K_;
;                     LT[i] = src[(size_t)k_ * N_ + n_];
;                 }
.LBB0_591:
	v_readlane_b32 s0, v255, 61
	s_cmp_lg_u32 s0, 0
	s_cbranch_scc1 .LBB0_627
	s_waitcnt vmcnt(5)
	v_lshl_add_u32 v32, s44, 9, v148
	s_mov_b32 s0, 0x40000
	v_cmp_gt_i32_e32 vcc, s0, v32
	s_and_saveexec_b64 s[0:1], vcc
	s_cbranch_execz .LBB0_612
	v_readlane_b32 s26, v254, 30
	v_readlane_b32 s27, v254, 31
	s_lshl_b64 s[24:25], s[26:27], 17
	s_waitcnt lgkmcnt(0)
	s_add_u32 s14, s20, s24
	s_addc_u32 s15, s21, s25
	s_add_u32 s20, s22, s24
	s_addc_u32 s21, s23, s25
	s_add_u32 s4, s4, s24
	s_addc_u32 s5, s5, s25
	s_add_u32 s6, s6, s24
	s_addc_u32 s7, s7, s25
	s_lshl_b64 s[22:23], s[26:27], 18
	s_add_u32 s8, s8, s22
	s_addc_u32 s9, s9, s23
	s_add_u32 s10, s10, s22
	s_addc_u32 s11, s11, s23
	s_lshl_b32 s22, s45, 9
	v_ashrrev_i32_e32 v33, 31, v32
	v_lshl_add_u64 v[0:1], v[32:33], 2, s[18:19]
	s_mov_b64 s[24:25], 0x29c00000
	s_ashr_i32 s23, s22, 31
	v_lshl_add_u64 v[0:1], v[0:1], 0, s[24:25]
	s_lshl_b64 s[24:25], s[22:23], 2
	s_mov_b64 s[26:27], 0
	s_waitcnt vmcnt(4)
	v_mov_b32_e32 v6, v32
	s_branch .LBB0_595

; __device__ __forceinline__ void xcd_barrier(const XcdBarrier& b) {
;     asm volatile("s_waitcnt vmcnt(0)" ::: "memory");
;     __syncthreads();
;     if (threadIdx.x == 0) {
;         unsigned* bar = b.bar;
;         __builtin_amdgcn_s_waitcnt(0);
;         unsigned nloc = b.st[0], nx = b.st[1];
;         if (nloc == 0u) { xcd_barrier_complete(bar, b.x, nloc, nx); b.st[0] = nloc; b.st[1] = nx; }
; __global__ void __launch_bounds__(NTHR, 2) hymba_fwd(Args args) {
;     ...
;         if (ph + 1 < hi) xcd_barrier(xbar);
.LBB0_627:
	s_add_i32 s12, s54, 1
	v_readlane_b32 s14, v254, 26
	s_cmp_ge_i32 s12, s55
	v_readlane_b32 s15, v254, 27
	s_waitcnt lgkmcnt(0)
	v_readlane_b32 s16, v254, 28
	s_cbranch_scc1 .LBB0_681
	v_readlane_b32 s0, v255, 62
	s_cmp_lg_u32 s0, 0
	s_cbranch_scc1 .LBB0_681
	s_waitcnt vmcnt(0)
	s_barrier
	s_mov_b64 s[0:1], exec
	v_readlane_b32 s4, v253, 5
	v_readlane_b32 s5, v253, 6
	s_and_b64 s[4:5], s[0:1], s[4:5]
	s_mov_b64 exec, s[4:5]
	s_cbranch_execz .LBB0_680
	v_readlane_b32 s4, v254, 24
	s_waitcnt vmcnt(0) expcnt(0) lgkmcnt(0)
	s_nop 0
	v_mov_b32_e32 v0, s4
	ds_read_b32 v2, v0
	v_readlane_b32 s4, v254, 25
	s_waitcnt lgkmcnt(0)
	v_cmp_ne_u32_e32 vcc, 0, v2
	v_mov_b32_e32 v0, s4
	ds_read_b32 v0, v0
	s_cbranch_vccnz .LBB0_644
	s_mov_b32 s10, 1
	s_branch .LBB0_632
